# v109 + ph_gu epilogue prefetches the row scales of the next row block (slot loads issued before the row math, reduced after the stores) when the next tile changes row block
# baseline (speedup 1.0000x reference)
; DI unsigned pk2(float lo, float hi) { unsigned r; asm("v_cvt_pk_bf16_f32 %0, %1, %2" : "=v"(r) : "v"(lo), "v"(hi)); return r; }
; DI float fsilu(float x) { return x * fsigmoid(x); }
;     DI void operator()(const f32x4 (&acc)[2][2][4][2], const Unit& u, int wr, int wc, int fr, int fq) const {
;     ...
;             for (int m = 0; m < 4; ++m) sl[ai][m] = *(const f32x4*)(slots + (size_t)(rowb + ai * HALF + m * 16) * 16 + 4 * fq);
;     ...
;             for (int m = 0; m < 4; ++m) {
;                 const int row = rowb + ai * HALF + m * 16;
;                 float t = (sl[ai][m][0] + sl[ai][m][1]) + (sl[ai][m][2] + sl[ai][m][3]);
;                 t += __shfl_xor(t, 16); t += __shfl_xor(t, 32);
;                 const float rs = __builtin_amdgcn_rsqf(t * (1.0f / D) + EPS);
;                 float h[8];
; #pragma unroll
;                 for (int n = 0; n < 2; ++n)
; #pragma unroll
;                     for (int j = 0; j < 4; ++j) { const float gv = acc[ai][0][m][n][j] * rs, uv = acc[ai][1][m][n][j] * rs; h[n * 4 + j] = fsilu(gv) * uv; }
;                 u32x4 w; w.x = pk2(h[0], h[1]); w.y = pk2(h[2], h[3]); w.z = pk2(h[4], h[5]); w.w = pk2(h[6], h[7]);
;                 *(u32x4*)(H + (size_t)row * FF + col0) = w;
.Lgu_rs_cached:
	s_mov_b32 s101, 0
	s_and_b64 vcc, exec, s[4:5]
	s_cbranch_vccz .Lgu_pf_skip
	s_cmp_eq_u32 s48, s54
	s_cbranch_scc1 .Lgu_pf_skip
	s_mov_b32 s101, 1
	v_lshl_add_u32 v102, s48, 8, v1
	v_lshlrev_b32_e32 v102, 6, v102
	v_mov_b32_e32 v103, 0
	v_add_u32_e32 v104, 0x2000, v102
	v_mov_b32_e32 v105, 0
	v_lshl_add_u64 v[182:183], v[160:161], 0, v[102:103]
	v_lshl_add_u64 v[122:123], v[160:161], 0, v[104:105]
	global_load_dwordx4 v[102:105], v[182:183], off
	global_load_dwordx4 v[132:135], v[182:183], off offset:1024
	global_load_dwordx4 v[140:143], v[182:183], off offset:2048
	global_load_dwordx4 v[144:147], v[182:183], off offset:3072
	global_load_dwordx4 v[148:151], v[122:123], off
	global_load_dwordx4 v[174:177], v[122:123], off offset:1024
	global_load_dwordx4 v[178:181], v[122:123], off offset:2048
	global_load_dwordx4 v[188:191], v[122:123], off offset:3072
.Lgu_pf_skip:
	v_pk_mul_f32 v[136:137], v[136:137], v[232:233] op_sel_hi:[1,0]
	v_pk_mul_f32 v[138:139], v[138:139], v[232:233] op_sel_hi:[1,0]
	v_pk_mul_f32 v[128:129], v[128:129], v[232:233] op_sel_hi:[1,0]
	v_pk_mul_f32 v[130:131], v[130:131], v[232:233] op_sel_hi:[1,0]
	v_pk_mul_f32 v[206:207], v[136:137], s[98:99] op_sel_hi:[1,0]
	v_pk_mul_f32 v[208:209], v[138:139], s[98:99] op_sel_hi:[1,0]
	v_pk_mul_f32 v[210:211], v[128:129], s[98:99] op_sel_hi:[1,0]
	v_pk_mul_f32 v[212:213], v[130:131], s[98:99] op_sel_hi:[1,0]
	v_pk_mul_f32 v[82:83], v[82:83], v[232:233] op_sel_hi:[1,0]
	v_pk_mul_f32 v[84:85], v[84:85], v[232:233] op_sel_hi:[1,0]
	v_pk_mul_f32 v[124:125], v[124:125], v[232:233] op_sel_hi:[1,0]
	v_pk_mul_f32 v[126:127], v[126:127], v[232:233] op_sel_hi:[1,0]
	v_exp_f32_e32 v206, v206
	v_exp_f32_e32 v207, v207
	v_exp_f32_e32 v208, v208
	v_exp_f32_e32 v209, v209
	v_exp_f32_e32 v210, v210
	v_exp_f32_e32 v211, v211
	v_exp_f32_e32 v212, v212
	v_exp_f32_e32 v213, v213
	v_pk_add_f32 v[206:207], v[206:207], s[100:101] op_sel_hi:[1,0]
	v_pk_add_f32 v[208:209], v[208:209], s[100:101] op_sel_hi:[1,0]
	v_pk_add_f32 v[210:211], v[210:211], s[100:101] op_sel_hi:[1,0]
	v_pk_add_f32 v[212:213], v[212:213], s[100:101] op_sel_hi:[1,0]
	v_rcp_f32_e32 v206, v206
	v_rcp_f32_e32 v207, v207
	v_rcp_f32_e32 v208, v208
	v_rcp_f32_e32 v209, v209
	v_rcp_f32_e32 v210, v210
	v_rcp_f32_e32 v211, v211
	v_rcp_f32_e32 v212, v212
	v_rcp_f32_e32 v213, v213
	v_pk_mul_f32 v[206:207], v[136:137], v[206:207]
	v_pk_mul_f32 v[208:209], v[138:139], v[208:209]
	v_pk_mul_f32 v[210:211], v[128:129], v[210:211]
	v_pk_mul_f32 v[212:213], v[130:131], v[212:213]
	v_pk_mul_f32 v[206:207], v[82:83], v[206:207]
	v_pk_mul_f32 v[208:209], v[84:85], v[208:209]
	v_pk_mul_f32 v[210:211], v[124:125], v[210:211]
	v_pk_mul_f32 v[212:213], v[126:127], v[212:213]
	v_cvt_pk_bf16_f32 v214, v206, v207
	v_cvt_pk_bf16_f32 v215, v208, v209
	v_cvt_pk_bf16_f32 v216, v210, v211
	v_cvt_pk_bf16_f32 v217, v212, v213
	global_store_dwordx4 v166, v[214:217], s[8:9]
	v_pk_mul_f32 v[118:119], v[118:119], v[232:233] op_sel:[0,1] op_sel_hi:[1,1]
	v_pk_mul_f32 v[120:121], v[120:121], v[232:233] op_sel:[0,1] op_sel_hi:[1,1]
	v_pk_mul_f32 v[110:111], v[110:111], v[232:233] op_sel:[0,1] op_sel_hi:[1,1]
	v_pk_mul_f32 v[112:113], v[112:113], v[232:233] op_sel:[0,1] op_sel_hi:[1,1]
	v_pk_mul_f32 v[218:219], v[118:119], s[98:99] op_sel_hi:[1,0]
	v_pk_mul_f32 v[220:221], v[120:121], s[98:99] op_sel_hi:[1,0]
	v_pk_mul_f32 v[222:223], v[110:111], s[98:99] op_sel_hi:[1,0]
	v_pk_mul_f32 v[224:225], v[112:113], s[98:99] op_sel_hi:[1,0]
	v_pk_mul_f32 v[114:115], v[114:115], v[232:233] op_sel:[0,1] op_sel_hi:[1,1]
	v_pk_mul_f32 v[116:117], v[116:117], v[232:233] op_sel:[0,1] op_sel_hi:[1,1]
	v_pk_mul_f32 v[106:107], v[106:107], v[232:233] op_sel:[0,1] op_sel_hi:[1,1]
	v_pk_mul_f32 v[108:109], v[108:109], v[232:233] op_sel:[0,1] op_sel_hi:[1,1]
	v_exp_f32_e32 v218, v218
	v_exp_f32_e32 v219, v219
	v_exp_f32_e32 v220, v220
	v_exp_f32_e32 v221, v221
	v_exp_f32_e32 v222, v222
	v_exp_f32_e32 v223, v223
	v_exp_f32_e32 v224, v224
	v_exp_f32_e32 v225, v225
	v_pk_add_f32 v[218:219], v[218:219], s[100:101] op_sel_hi:[1,0]
	v_pk_add_f32 v[220:221], v[220:221], s[100:101] op_sel_hi:[1,0]
	v_pk_add_f32 v[222:223], v[222:223], s[100:101] op_sel_hi:[1,0]
	v_pk_add_f32 v[224:225], v[224:225], s[100:101] op_sel_hi:[1,0]
	v_rcp_f32_e32 v218, v218
	v_rcp_f32_e32 v219, v219
	v_rcp_f32_e32 v220, v220
	v_rcp_f32_e32 v221, v221
	v_rcp_f32_e32 v222, v222
	v_rcp_f32_e32 v223, v223
	v_rcp_f32_e32 v224, v224
	v_rcp_f32_e32 v225, v225
	v_pk_mul_f32 v[218:219], v[118:119], v[218:219]
	v_pk_mul_f32 v[220:221], v[120:121], v[220:221]
	v_pk_mul_f32 v[222:223], v[110:111], v[222:223]
	v_pk_mul_f32 v[224:225], v[112:113], v[224:225]
	v_pk_mul_f32 v[218:219], v[114:115], v[218:219]
	v_pk_mul_f32 v[220:221], v[116:117], v[220:221]
	v_pk_mul_f32 v[222:223], v[106:107], v[222:223]
	v_pk_mul_f32 v[224:225], v[108:109], v[224:225]
	v_cvt_pk_bf16_f32 v200, v218, v219
	v_cvt_pk_bf16_f32 v201, v220, v221
	v_cvt_pk_bf16_f32 v202, v222, v223
	v_cvt_pk_bf16_f32 v203, v224, v225
	global_store_dwordx4 v167, v[200:203], s[8:9]
	v_pk_mul_f32 v[98:99], v[98:99], v[234:235] op_sel_hi:[1,0]
	v_pk_mul_f32 v[100:101], v[100:101], v[234:235] op_sel_hi:[1,0]
	v_pk_mul_f32 v[90:91], v[90:91], v[234:235] op_sel_hi:[1,0]
	v_pk_mul_f32 v[92:93], v[92:93], v[234:235] op_sel_hi:[1,0]
	v_pk_mul_f32 v[206:207], v[98:99], s[98:99] op_sel_hi:[1,0]
	v_pk_mul_f32 v[208:209], v[100:101], s[98:99] op_sel_hi:[1,0]
	v_pk_mul_f32 v[210:211], v[90:91], s[98:99] op_sel_hi:[1,0]
	v_pk_mul_f32 v[212:213], v[92:93], s[98:99] op_sel_hi:[1,0]
	v_pk_mul_f32 v[94:95], v[94:95], v[234:235] op_sel_hi:[1,0]
	v_pk_mul_f32 v[96:97], v[96:97], v[234:235] op_sel_hi:[1,0]
; DI unsigned pk2(float lo, float hi) { unsigned r; asm("v_cvt_pk_bf16_f32 %0, %1, %2" : "=v"(r) : "v"(lo), "v"(hi)); return r; }
; DI float fsilu(float x) { return x * fsigmoid(x); }
;     DI void operator()(const f32x4 (&acc)[2][2][4][2], const Unit& u, int wr, int wc, int fr, int fq) const {
;     ...
;             for (int m = 0; m < 4; ++m) {
;                 const int row = rowb + ai * HALF + m * 16;
;                 float t = (sl[ai][m][0] + sl[ai][m][1]) + (sl[ai][m][2] + sl[ai][m][3]);
;                 t += __shfl_xor(t, 16); t += __shfl_xor(t, 32);
;                 const float rs = __builtin_amdgcn_rsqf(t * (1.0f / D) + EPS);
;                 float h[8];
; #pragma unroll
;                 for (int n = 0; n < 2; ++n)
; #pragma unroll
;                     for (int j = 0; j < 4; ++j) { const float gv = acc[ai][0][m][n][j] * rs, uv = acc[ai][1][m][n][j] * rs; h[n * 4 + j] = fsilu(gv) * uv; }
;                 u32x4 w; w.x = pk2(h[0], h[1]); w.y = pk2(h[2], h[3]); w.z = pk2(h[4], h[5]); w.w = pk2(h[6], h[7]);
;                 *(u32x4*)(H + (size_t)row * FF + col0) = w;
	v_pk_mul_f32 v[86:87], v[86:87], v[234:235] op_sel_hi:[1,0]
	v_pk_mul_f32 v[88:89], v[88:89], v[234:235] op_sel_hi:[1,0]
	v_exp_f32_e32 v206, v206
	v_exp_f32_e32 v207, v207
	v_exp_f32_e32 v208, v208
	v_exp_f32_e32 v209, v209
	v_exp_f32_e32 v210, v210
	v_exp_f32_e32 v211, v211
	v_exp_f32_e32 v212, v212
	v_exp_f32_e32 v213, v213
	v_pk_add_f32 v[206:207], v[206:207], s[100:101] op_sel_hi:[1,0]
	v_pk_add_f32 v[208:209], v[208:209], s[100:101] op_sel_hi:[1,0]
	v_pk_add_f32 v[210:211], v[210:211], s[100:101] op_sel_hi:[1,0]
	v_pk_add_f32 v[212:213], v[212:213], s[100:101] op_sel_hi:[1,0]
	v_rcp_f32_e32 v206, v206
	v_rcp_f32_e32 v207, v207
	v_rcp_f32_e32 v208, v208
	v_rcp_f32_e32 v209, v209
	v_rcp_f32_e32 v210, v210
	v_rcp_f32_e32 v211, v211
	v_rcp_f32_e32 v212, v212
	v_rcp_f32_e32 v213, v213
	v_pk_mul_f32 v[206:207], v[98:99], v[206:207]
	v_pk_mul_f32 v[208:209], v[100:101], v[208:209]
	v_pk_mul_f32 v[210:211], v[90:91], v[210:211]
	v_pk_mul_f32 v[212:213], v[92:93], v[212:213]
	v_pk_mul_f32 v[206:207], v[94:95], v[206:207]
	v_pk_mul_f32 v[208:209], v[96:97], v[208:209]
	v_pk_mul_f32 v[210:211], v[86:87], v[210:211]
	v_pk_mul_f32 v[212:213], v[88:89], v[212:213]
	v_cvt_pk_bf16_f32 v214, v206, v207
	v_cvt_pk_bf16_f32 v215, v208, v209
	v_cvt_pk_bf16_f32 v216, v210, v211
	v_cvt_pk_bf16_f32 v217, v212, v213
	global_store_dwordx4 v168, v[214:217], s[8:9]
	v_pk_mul_f32 v[78:79], v[78:79], v[234:235] op_sel:[0,1] op_sel_hi:[1,1]
	v_pk_mul_f32 v[80:81], v[80:81], v[234:235] op_sel:[0,1] op_sel_hi:[1,1]
	v_pk_mul_f32 v[70:71], v[70:71], v[234:235] op_sel:[0,1] op_sel_hi:[1,1]
	v_pk_mul_f32 v[72:73], v[72:73], v[234:235] op_sel:[0,1] op_sel_hi:[1,1]
	v_pk_mul_f32 v[218:219], v[78:79], s[98:99] op_sel_hi:[1,0]
	v_pk_mul_f32 v[220:221], v[80:81], s[98:99] op_sel_hi:[1,0]
	v_pk_mul_f32 v[222:223], v[70:71], s[98:99] op_sel_hi:[1,0]
	v_pk_mul_f32 v[224:225], v[72:73], s[98:99] op_sel_hi:[1,0]
	v_pk_mul_f32 v[74:75], v[74:75], v[234:235] op_sel:[0,1] op_sel_hi:[1,1]
	v_pk_mul_f32 v[76:77], v[76:77], v[234:235] op_sel:[0,1] op_sel_hi:[1,1]
	v_pk_mul_f32 v[66:67], v[66:67], v[234:235] op_sel:[0,1] op_sel_hi:[1,1]
	v_pk_mul_f32 v[68:69], v[68:69], v[234:235] op_sel:[0,1] op_sel_hi:[1,1]
	v_exp_f32_e32 v218, v218
	v_exp_f32_e32 v219, v219
	v_exp_f32_e32 v220, v220
	v_exp_f32_e32 v221, v221
	v_exp_f32_e32 v222, v222
	v_exp_f32_e32 v223, v223
	v_exp_f32_e32 v224, v224
	v_exp_f32_e32 v225, v225
	v_pk_add_f32 v[218:219], v[218:219], s[100:101] op_sel_hi:[1,0]
	v_pk_add_f32 v[220:221], v[220:221], s[100:101] op_sel_hi:[1,0]
	v_pk_add_f32 v[222:223], v[222:223], s[100:101] op_sel_hi:[1,0]
	v_pk_add_f32 v[224:225], v[224:225], s[100:101] op_sel_hi:[1,0]
	v_rcp_f32_e32 v218, v218
	v_rcp_f32_e32 v219, v219
	v_rcp_f32_e32 v220, v220
	v_rcp_f32_e32 v221, v221
	v_rcp_f32_e32 v222, v222
	v_rcp_f32_e32 v223, v223
	v_rcp_f32_e32 v224, v224
	v_rcp_f32_e32 v225, v225
	v_pk_mul_f32 v[218:219], v[78:79], v[218:219]
	v_pk_mul_f32 v[220:221], v[80:81], v[220:221]
	v_pk_mul_f32 v[222:223], v[70:71], v[222:223]
	v_pk_mul_f32 v[224:225], v[72:73], v[224:225]
	v_pk_mul_f32 v[218:219], v[74:75], v[218:219]
	v_pk_mul_f32 v[220:221], v[76:77], v[220:221]
	v_pk_mul_f32 v[222:223], v[66:67], v[222:223]
	v_pk_mul_f32 v[224:225], v[68:69], v[224:225]
	v_cvt_pk_bf16_f32 v200, v218, v219
	v_cvt_pk_bf16_f32 v201, v220, v221
	v_cvt_pk_bf16_f32 v202, v222, v223
	v_cvt_pk_bf16_f32 v203, v224, v225
	global_store_dwordx4 v169, v[200:203], s[8:9]
	v_pk_mul_f32 v[62:63], v[62:63], v[236:237] op_sel_hi:[1,0]
	v_pk_mul_f32 v[64:65], v[64:65], v[236:237] op_sel_hi:[1,0]
	v_pk_mul_f32 v[54:55], v[54:55], v[236:237] op_sel_hi:[1,0]
	v_pk_mul_f32 v[56:57], v[56:57], v[236:237] op_sel_hi:[1,0]
	v_pk_mul_f32 v[206:207], v[62:63], s[98:99] op_sel_hi:[1,0]
	v_pk_mul_f32 v[208:209], v[64:65], s[98:99] op_sel_hi:[1,0]
	v_pk_mul_f32 v[210:211], v[54:55], s[98:99] op_sel_hi:[1,0]
	v_pk_mul_f32 v[212:213], v[56:57], s[98:99] op_sel_hi:[1,0]
	v_pk_mul_f32 v[58:59], v[58:59], v[236:237] op_sel_hi:[1,0]
	v_pk_mul_f32 v[60:61], v[60:61], v[236:237] op_sel_hi:[1,0]
	v_pk_mul_f32 v[50:51], v[50:51], v[236:237] op_sel_hi:[1,0]
	v_pk_mul_f32 v[52:53], v[52:53], v[236:237] op_sel_hi:[1,0]
	v_exp_f32_e32 v206, v206
	v_exp_f32_e32 v207, v207
	v_exp_f32_e32 v208, v208
	v_exp_f32_e32 v209, v209
	v_exp_f32_e32 v210, v210
	v_exp_f32_e32 v211, v211
	v_exp_f32_e32 v212, v212
	v_exp_f32_e32 v213, v213
	v_pk_add_f32 v[206:207], v[206:207], s[100:101] op_sel_hi:[1,0]
	v_pk_add_f32 v[208:209], v[208:209], s[100:101] op_sel_hi:[1,0]
	v_pk_add_f32 v[210:211], v[210:211], s[100:101] op_sel_hi:[1,0]
	v_pk_add_f32 v[212:213], v[212:213], s[100:101] op_sel_hi:[1,0]
	v_rcp_f32_e32 v206, v206
	v_rcp_f32_e32 v207, v207
	v_rcp_f32_e32 v208, v208
	v_rcp_f32_e32 v209, v209
	v_rcp_f32_e32 v210, v210
	v_rcp_f32_e32 v211, v211
	v_rcp_f32_e32 v212, v212
	v_rcp_f32_e32 v213, v213
	v_pk_mul_f32 v[206:207], v[62:63], v[206:207]
	v_pk_mul_f32 v[208:209], v[64:65], v[208:209]
	v_pk_mul_f32 v[210:211], v[54:55], v[210:211]
	v_pk_mul_f32 v[212:213], v[56:57], v[212:213]
	v_pk_mul_f32 v[206:207], v[58:59], v[206:207]
	v_pk_mul_f32 v[208:209], v[60:61], v[208:209]
	v_pk_mul_f32 v[210:211], v[50:51], v[210:211]
	v_pk_mul_f32 v[212:213], v[52:53], v[212:213]
	v_cvt_pk_bf16_f32 v214, v206, v207
	v_cvt_pk_bf16_f32 v215, v208, v209
	v_cvt_pk_bf16_f32 v216, v210, v211
	v_cvt_pk_bf16_f32 v217, v212, v213
	global_store_dwordx4 v170, v[214:217], s[8:9]
	v_pk_mul_f32 v[46:47], v[46:47], v[236:237] op_sel:[0,1] op_sel_hi:[1,1]
	v_pk_mul_f32 v[48:49], v[48:49], v[236:237] op_sel:[0,1] op_sel_hi:[1,1]
	v_pk_mul_f32 v[38:39], v[38:39], v[236:237] op_sel:[0,1] op_sel_hi:[1,1]
; DI unsigned pk2(float lo, float hi) { unsigned r; asm("v_cvt_pk_bf16_f32 %0, %1, %2" : "=v"(r) : "v"(lo), "v"(hi)); return r; }
; DI float fsilu(float x) { return x * fsigmoid(x); }
;     DI void operator()(const f32x4 (&acc)[2][2][4][2], const Unit& u, int wr, int wc, int fr, int fq) const {
;     ...
;             for (int m = 0; m < 4; ++m) {
;                 const int row = rowb + ai * HALF + m * 16;
;                 float t = (sl[ai][m][0] + sl[ai][m][1]) + (sl[ai][m][2] + sl[ai][m][3]);
;                 t += __shfl_xor(t, 16); t += __shfl_xor(t, 32);
;                 const float rs = __builtin_amdgcn_rsqf(t * (1.0f / D) + EPS);
;                 float h[8];
; #pragma unroll
;                 for (int n = 0; n < 2; ++n)
; #pragma unroll
;                     for (int j = 0; j < 4; ++j) { const float gv = acc[ai][0][m][n][j] * rs, uv = acc[ai][1][m][n][j] * rs; h[n * 4 + j] = fsilu(gv) * uv; }
;                 u32x4 w; w.x = pk2(h[0], h[1]); w.y = pk2(h[2], h[3]); w.z = pk2(h[4], h[5]); w.w = pk2(h[6], h[7]);
;                 *(u32x4*)(H + (size_t)row * FF + col0) = w;
	v_pk_mul_f32 v[40:41], v[40:41], v[236:237] op_sel:[0,1] op_sel_hi:[1,1]
	v_pk_mul_f32 v[218:219], v[46:47], s[98:99] op_sel_hi:[1,0]
	v_pk_mul_f32 v[220:221], v[48:49], s[98:99] op_sel_hi:[1,0]
	v_pk_mul_f32 v[222:223], v[38:39], s[98:99] op_sel_hi:[1,0]
	v_pk_mul_f32 v[224:225], v[40:41], s[98:99] op_sel_hi:[1,0]
	v_pk_mul_f32 v[42:43], v[42:43], v[236:237] op_sel:[0,1] op_sel_hi:[1,1]
	v_pk_mul_f32 v[44:45], v[44:45], v[236:237] op_sel:[0,1] op_sel_hi:[1,1]
	v_pk_mul_f32 v[34:35], v[34:35], v[236:237] op_sel:[0,1] op_sel_hi:[1,1]
	v_pk_mul_f32 v[36:37], v[36:37], v[236:237] op_sel:[0,1] op_sel_hi:[1,1]
	v_exp_f32_e32 v218, v218
	v_exp_f32_e32 v219, v219
	v_exp_f32_e32 v220, v220
	v_exp_f32_e32 v221, v221
	v_exp_f32_e32 v222, v222
	v_exp_f32_e32 v223, v223
	v_exp_f32_e32 v224, v224
	v_exp_f32_e32 v225, v225
	v_pk_add_f32 v[218:219], v[218:219], s[100:101] op_sel_hi:[1,0]
	v_pk_add_f32 v[220:221], v[220:221], s[100:101] op_sel_hi:[1,0]
	v_pk_add_f32 v[222:223], v[222:223], s[100:101] op_sel_hi:[1,0]
	v_pk_add_f32 v[224:225], v[224:225], s[100:101] op_sel_hi:[1,0]
	v_rcp_f32_e32 v218, v218
	v_rcp_f32_e32 v219, v219
	v_rcp_f32_e32 v220, v220
	v_rcp_f32_e32 v221, v221
	v_rcp_f32_e32 v222, v222
	v_rcp_f32_e32 v223, v223
	v_rcp_f32_e32 v224, v224
	v_rcp_f32_e32 v225, v225
	v_pk_mul_f32 v[218:219], v[46:47], v[218:219]
	v_pk_mul_f32 v[220:221], v[48:49], v[220:221]
	v_pk_mul_f32 v[222:223], v[38:39], v[222:223]
	v_pk_mul_f32 v[224:225], v[40:41], v[224:225]
	v_pk_mul_f32 v[218:219], v[42:43], v[218:219]
	v_pk_mul_f32 v[220:221], v[44:45], v[220:221]
	v_pk_mul_f32 v[222:223], v[34:35], v[222:223]
	v_pk_mul_f32 v[224:225], v[36:37], v[224:225]
	v_cvt_pk_bf16_f32 v200, v218, v219
	v_cvt_pk_bf16_f32 v201, v220, v221
	v_cvt_pk_bf16_f32 v202, v222, v223
	v_cvt_pk_bf16_f32 v203, v224, v225
	global_store_dwordx4 v171, v[200:203], s[8:9]
	v_pk_mul_f32 v[30:31], v[30:31], v[238:239] op_sel_hi:[1,0]
	v_pk_mul_f32 v[32:33], v[32:33], v[238:239] op_sel_hi:[1,0]
	v_pk_mul_f32 v[22:23], v[22:23], v[238:239] op_sel_hi:[1,0]
	v_pk_mul_f32 v[24:25], v[24:25], v[238:239] op_sel_hi:[1,0]
	v_pk_mul_f32 v[206:207], v[30:31], s[98:99] op_sel_hi:[1,0]
	v_pk_mul_f32 v[208:209], v[32:33], s[98:99] op_sel_hi:[1,0]
	v_pk_mul_f32 v[210:211], v[22:23], s[98:99] op_sel_hi:[1,0]
	v_pk_mul_f32 v[212:213], v[24:25], s[98:99] op_sel_hi:[1,0]
	v_pk_mul_f32 v[26:27], v[26:27], v[238:239] op_sel_hi:[1,0]
	v_pk_mul_f32 v[28:29], v[28:29], v[238:239] op_sel_hi:[1,0]
	v_pk_mul_f32 v[18:19], v[18:19], v[238:239] op_sel_hi:[1,0]
	v_pk_mul_f32 v[20:21], v[20:21], v[238:239] op_sel_hi:[1,0]
	v_exp_f32_e32 v206, v206
	v_exp_f32_e32 v207, v207
	v_exp_f32_e32 v208, v208
	v_exp_f32_e32 v209, v209
	v_exp_f32_e32 v210, v210
	v_exp_f32_e32 v211, v211
	v_exp_f32_e32 v212, v212
	v_exp_f32_e32 v213, v213
	v_pk_add_f32 v[206:207], v[206:207], s[100:101] op_sel_hi:[1,0]
	v_pk_add_f32 v[208:209], v[208:209], s[100:101] op_sel_hi:[1,0]
	v_pk_add_f32 v[210:211], v[210:211], s[100:101] op_sel_hi:[1,0]
	v_pk_add_f32 v[212:213], v[212:213], s[100:101] op_sel_hi:[1,0]
	v_rcp_f32_e32 v206, v206
	v_rcp_f32_e32 v207, v207
	v_rcp_f32_e32 v208, v208
	v_rcp_f32_e32 v209, v209
	v_rcp_f32_e32 v210, v210
	v_rcp_f32_e32 v211, v211
	v_rcp_f32_e32 v212, v212
	v_rcp_f32_e32 v213, v213
	v_pk_mul_f32 v[206:207], v[30:31], v[206:207]
	v_pk_mul_f32 v[208:209], v[32:33], v[208:209]
	v_pk_mul_f32 v[210:211], v[22:23], v[210:211]
	v_pk_mul_f32 v[212:213], v[24:25], v[212:213]
	v_pk_mul_f32 v[206:207], v[26:27], v[206:207]
	v_pk_mul_f32 v[208:209], v[28:29], v[208:209]
	v_pk_mul_f32 v[210:211], v[18:19], v[210:211]
	v_pk_mul_f32 v[212:213], v[20:21], v[212:213]
	v_cvt_pk_bf16_f32 v214, v206, v207
	v_cvt_pk_bf16_f32 v215, v208, v209
	v_cvt_pk_bf16_f32 v216, v210, v211
	v_cvt_pk_bf16_f32 v217, v212, v213
	global_store_dwordx4 v172, v[214:217], s[8:9]
	v_pk_mul_f32 v[14:15], v[14:15], v[238:239] op_sel:[0,1] op_sel_hi:[1,1]
	v_pk_mul_f32 v[16:17], v[16:17], v[238:239] op_sel:[0,1] op_sel_hi:[1,1]
	v_pk_mul_f32 v[6:7], v[6:7], v[238:239] op_sel:[0,1] op_sel_hi:[1,1]
	v_pk_mul_f32 v[8:9], v[8:9], v[238:239] op_sel:[0,1] op_sel_hi:[1,1]
	v_pk_mul_f32 v[218:219], v[14:15], s[98:99] op_sel_hi:[1,0]
	v_pk_mul_f32 v[220:221], v[16:17], s[98:99] op_sel_hi:[1,0]
	v_pk_mul_f32 v[222:223], v[6:7], s[98:99] op_sel_hi:[1,0]
	v_pk_mul_f32 v[224:225], v[8:9], s[98:99] op_sel_hi:[1,0]
	v_pk_mul_f32 v[10:11], v[10:11], v[238:239] op_sel:[0,1] op_sel_hi:[1,1]
	v_pk_mul_f32 v[12:13], v[12:13], v[238:239] op_sel:[0,1] op_sel_hi:[1,1]
	v_pk_mul_f32 v[2:3], v[2:3], v[238:239] op_sel:[0,1] op_sel_hi:[1,1]
	v_pk_mul_f32 v[4:5], v[4:5], v[238:239] op_sel:[0,1] op_sel_hi:[1,1]
	v_exp_f32_e32 v218, v218
	v_exp_f32_e32 v219, v219
	v_exp_f32_e32 v220, v220
	v_exp_f32_e32 v221, v221
	v_exp_f32_e32 v222, v222
	v_exp_f32_e32 v223, v223
	v_exp_f32_e32 v224, v224
	v_exp_f32_e32 v225, v225
	v_pk_add_f32 v[218:219], v[218:219], s[100:101] op_sel_hi:[1,0]
	v_pk_add_f32 v[220:221], v[220:221], s[100:101] op_sel_hi:[1,0]
	v_pk_add_f32 v[222:223], v[222:223], s[100:101] op_sel_hi:[1,0]
	v_pk_add_f32 v[224:225], v[224:225], s[100:101] op_sel_hi:[1,0]
	v_rcp_f32_e32 v218, v218
	v_rcp_f32_e32 v219, v219
	v_rcp_f32_e32 v220, v220
	v_rcp_f32_e32 v221, v221
	v_rcp_f32_e32 v222, v222
	v_rcp_f32_e32 v223, v223
	v_rcp_f32_e32 v224, v224
	v_rcp_f32_e32 v225, v225
	v_pk_mul_f32 v[218:219], v[14:15], v[218:219]
	v_pk_mul_f32 v[220:221], v[16:17], v[220:221]
	v_pk_mul_f32 v[222:223], v[6:7], v[222:223]
	v_pk_mul_f32 v[224:225], v[8:9], v[224:225]
	v_pk_mul_f32 v[218:219], v[10:11], v[218:219]
	v_pk_mul_f32 v[220:221], v[12:13], v[220:221]
	v_pk_mul_f32 v[222:223], v[2:3], v[222:223]
	v_pk_mul_f32 v[224:225], v[4:5], v[224:225]
	v_cvt_pk_bf16_f32 v200, v218, v219
	v_cvt_pk_bf16_f32 v201, v220, v221
	v_cvt_pk_bf16_f32 v202, v222, v223
	v_cvt_pk_bf16_f32 v203, v224, v225
	global_store_dwordx4 v173, v[200:203], s[8:9]
	s_cmp_eq_u32 s101, 1
	s_cbranch_scc0 .Lgu_pf_done
;     DI void operator()(const f32x4 (&acc)[2][2][4][2], const Unit& u, int wr, int wc, int fr, int fq) const {
;     ...
;             for (int m = 0; m < 4; ++m) sl[ai][m] = *(const f32x4*)(slots + (size_t)(rowb + ai * HALF + m * 16) * 16 + 4 * fq);
;         asm volatile("" ::: "memory");
; #pragma unroll
;         for (int ai = 0; ai < 2; ++ai)
; #pragma unroll
;             for (int m = 0; m < 4; ++m) {
;                 const int row = rowb + ai * HALF + m * 16;
;                 float t = (sl[ai][m][0] + sl[ai][m][1]) + (sl[ai][m][2] + sl[ai][m][3]);
;                 t += __shfl_xor(t, 16); t += __shfl_xor(t, 32);
;                 const float rs = __builtin_amdgcn_rsqf(t * (1.0f / D) + EPS);
	v_xor_b32_e32 v204, 16, v249
	v_xor_b32_e32 v205, 32, v249
	v_lshlrev_b32_e32 v204, 2, v204
	v_lshlrev_b32_e32 v205, 2, v205
	s_mov_b32 s99, s48
	s_waitcnt vmcnt(15)
	v_add_f32_e32 v102, v102, v103
	v_add_f32_e32 v104, v104, v105
	v_add_f32_e32 v102, v102, v104
	ds_bpermute_b32 v103, v204, v102
	s_waitcnt vmcnt(14)
	v_add_f32_e32 v132, v132, v133
	v_add_f32_e32 v134, v134, v135
	v_add_f32_e32 v132, v132, v134
	ds_bpermute_b32 v133, v204, v132
	s_waitcnt vmcnt(13)
	v_add_f32_e32 v140, v140, v141
	v_add_f32_e32 v142, v142, v143
	v_add_f32_e32 v140, v140, v142
	ds_bpermute_b32 v141, v204, v140
	s_waitcnt vmcnt(12)
	v_add_f32_e32 v144, v144, v145
	v_add_f32_e32 v146, v146, v147
	v_add_f32_e32 v144, v144, v146
	ds_bpermute_b32 v145, v204, v144
	s_waitcnt vmcnt(11)
	v_add_f32_e32 v148, v148, v149
	v_add_f32_e32 v150, v150, v151
	v_add_f32_e32 v148, v148, v150
	ds_bpermute_b32 v149, v204, v148
	s_waitcnt vmcnt(10)
	v_add_f32_e32 v174, v174, v175
	v_add_f32_e32 v176, v176, v177
	v_add_f32_e32 v174, v174, v176
	ds_bpermute_b32 v175, v204, v174
	s_waitcnt vmcnt(9)
	v_add_f32_e32 v178, v178, v179
	v_add_f32_e32 v180, v180, v181
	v_add_f32_e32 v178, v178, v180
	ds_bpermute_b32 v179, v204, v178
	s_waitcnt vmcnt(8)
	v_add_f32_e32 v188, v188, v189
	v_add_f32_e32 v190, v190, v191
	v_add_f32_e32 v188, v188, v190
	ds_bpermute_b32 v189, v204, v188
	s_waitcnt lgkmcnt(0)
	v_add_f32_e32 v102, v102, v103
	ds_bpermute_b32 v103, v205, v102
	v_add_f32_e32 v132, v132, v133
	ds_bpermute_b32 v133, v205, v132
	v_add_f32_e32 v140, v140, v141
	ds_bpermute_b32 v141, v205, v140
	v_add_f32_e32 v144, v144, v145
	ds_bpermute_b32 v145, v205, v144
	v_add_f32_e32 v148, v148, v149
	ds_bpermute_b32 v149, v205, v148
	v_add_f32_e32 v174, v174, v175
	ds_bpermute_b32 v175, v205, v174
	v_add_f32_e32 v178, v178, v179
	ds_bpermute_b32 v179, v205, v178
	v_add_f32_e32 v188, v188, v189
	ds_bpermute_b32 v189, v205, v188
	s_waitcnt lgkmcnt(0)
	v_add_f32_e32 v102, v102, v103
	v_add_f32_e32 v132, v132, v133
	v_add_f32_e32 v140, v140, v141
	v_add_f32_e32 v144, v144, v145
	v_add_f32_e32 v148, v148, v149
	v_add_f32_e32 v174, v174, v175
	v_add_f32_e32 v178, v178, v179
	v_add_f32_e32 v188, v188, v189
	v_fmamk_f32 v102, v102, 0x3a800000, v243
	v_fmamk_f32 v132, v132, 0x3a800000, v243
	v_fmamk_f32 v140, v140, 0x3a800000, v243
	v_fmamk_f32 v144, v144, 0x3a800000, v243
	v_fmamk_f32 v148, v148, 0x3a800000, v243
	v_fmamk_f32 v174, v174, 0x3a800000, v243
	v_fmamk_f32 v178, v178, 0x3a800000, v243
	v_fmamk_f32 v188, v188, 0x3a800000, v243
	v_rsq_f32_e32 v232, v102
	v_rsq_f32_e32 v233, v132
	v_rsq_f32_e32 v234, v140
	v_rsq_f32_e32 v235, v144
	v_rsq_f32_e32 v236, v148
	v_rsq_f32_e32 v237, v174
	v_rsq_f32_e32 v238, v178
	v_rsq_f32_e32 v239, v188
.Lgu_pf_done:
	s_andn2_b64 vcc, exec, s[4:5]
	s_mov_b64 s[4:5], -1
	s_cbranch_vccnz .LBB0_697
	s_andn2_b64 vcc, exec, s[6:7]
	s_cbranch_vccnz .LBB0_696
	s_barrier
	s_branch .LBB0_696
